# per-tile GEMM prologue: the second (redundant) zeroing of the 128 accumulator registers removed in all seven template instances
# speedup vs baseline: 1.0068x; 1.0068x over previous
; template <class Epi>
; __device__ __forceinline__ void gemm_phase(LAS unsigned char* lds, const Gemm g, const StaticOrder& S, const Epi& E) {
;     ...
;         const bool has_next = S.next(ui + 1, nxt);
;         const char* nA = has_next ? (const char*)g.A + (size_t)nxt.pm * tstep : cA; const char* nB = has_next ? (const char*)g.Bt + (size_t)nxt.pn * tstep : cB;
;         for (int t = 0; t < nt; t += 2) {
;             const bool last = (t == nt - 2);
;             const char* a1 = cA + (size_t)(t + 1) * kstep;
;             const char* a2 = last ? nA : cA + (size_t)(t + 2) * kstep; const char* b2 = last ? nB : cB + (size_t)(t + 2) * kstep;
;     ...
; #pragma unroll
;         for (int a = 0; a < 2; ++a)
; #pragma unroll
;             for (int b = 0; b < 2; ++b)
; #pragma unroll
;                 for (int m = 0; m < 4; ++m)
; #pragma unroll
;                     for (int n = 0; n < 2; ++n) acc[a][b][m][n] = (f32x4){0.f, 0.f, 0.f, 0.f};
;         cur = nxt; cA = nA; cB = nB; ++ui;
.LBB0_45:
	v_mov_b32_e32 v125, 0
	s_andn2_b64 vcc, exec, s[10:11]
	v_mov_b32_e32 v124, v125
	v_mov_b32_e32 v123, v125
	v_mov_b32_e32 v122, v125
	v_mov_b32_e32 v129, v125
	v_mov_b32_e32 v128, v125
	v_mov_b32_e32 v127, v125
	v_mov_b32_e32 v126, v125
	v_mov_b32_e32 v113, v125
	v_mov_b32_e32 v112, v125
	v_mov_b32_e32 v111, v125
	v_mov_b32_e32 v110, v125
	v_mov_b32_e32 v109, v125
	v_mov_b32_e32 v108, v125
	v_mov_b32_e32 v107, v125
	v_mov_b32_e32 v106, v125
	v_mov_b32_e32 v97, v125
	v_mov_b32_e32 v96, v125
	v_mov_b32_e32 v95, v125
	v_mov_b32_e32 v94, v125
	v_mov_b32_e32 v93, v125
	v_mov_b32_e32 v92, v125
	v_mov_b32_e32 v91, v125
	v_mov_b32_e32 v90, v125
	v_mov_b32_e32 v81, v125
	v_mov_b32_e32 v80, v125
	v_mov_b32_e32 v79, v125
	v_mov_b32_e32 v78, v125
	v_mov_b32_e32 v77, v125
	v_mov_b32_e32 v76, v125
	v_mov_b32_e32 v75, v125
	v_mov_b32_e32 v74, v125
	v_mov_b32_e32 v121, v125
	v_mov_b32_e32 v120, v125
	v_mov_b32_e32 v119, v125
	v_mov_b32_e32 v118, v125
	v_mov_b32_e32 v117, v125
	v_mov_b32_e32 v116, v125
	v_mov_b32_e32 v115, v125
	v_mov_b32_e32 v114, v125
	v_mov_b32_e32 v105, v125
	v_mov_b32_e32 v104, v125
	v_mov_b32_e32 v103, v125
	v_mov_b32_e32 v102, v125
	v_mov_b32_e32 v101, v125
	v_mov_b32_e32 v100, v125
	v_mov_b32_e32 v99, v125
	v_mov_b32_e32 v98, v125
	v_mov_b32_e32 v89, v125
	v_mov_b32_e32 v88, v125
	v_mov_b32_e32 v87, v125
	v_mov_b32_e32 v86, v125
	v_mov_b32_e32 v85, v125
	v_mov_b32_e32 v84, v125
	v_mov_b32_e32 v83, v125
	v_mov_b32_e32 v82, v125
	v_mov_b32_e32 v73, v125
	v_mov_b32_e32 v72, v125
	v_mov_b32_e32 v71, v125
	v_mov_b32_e32 v70, v125
	v_mov_b32_e32 v69, v125
	v_mov_b32_e32 v68, v125
	v_mov_b32_e32 v67, v125
	v_mov_b32_e32 v66, v125
	v_mov_b32_e32 v65, v125
	v_mov_b32_e32 v64, v125
	v_mov_b32_e32 v63, v125
	v_mov_b32_e32 v62, v125
	v_mov_b32_e32 v61, v125
	v_mov_b32_e32 v60, v125
	v_mov_b32_e32 v59, v125
	v_mov_b32_e32 v58, v125
	v_mov_b32_e32 v49, v125
	v_mov_b32_e32 v48, v125
	v_mov_b32_e32 v47, v125
	v_mov_b32_e32 v46, v125
	v_mov_b32_e32 v45, v125
	v_mov_b32_e32 v44, v125
	v_mov_b32_e32 v43, v125
	v_mov_b32_e32 v42, v125
	v_mov_b32_e32 v33, v125
	v_mov_b32_e32 v32, v125
	v_mov_b32_e32 v31, v125
	v_mov_b32_e32 v30, v125
	v_mov_b32_e32 v29, v125
	v_mov_b32_e32 v28, v125
	v_mov_b32_e32 v27, v125
	v_mov_b32_e32 v26, v125
	v_mov_b32_e32 v17, v125
	v_mov_b32_e32 v16, v125
	v_mov_b32_e32 v15, v125
	v_mov_b32_e32 v14, v125
	v_mov_b32_e32 v13, v125
	v_mov_b32_e32 v12, v125
	v_mov_b32_e32 v11, v125
	v_mov_b32_e32 v10, v125
	v_mov_b32_e32 v57, v125
	v_mov_b32_e32 v56, v125
	v_mov_b32_e32 v55, v125
	v_mov_b32_e32 v54, v125
	v_mov_b32_e32 v53, v125
	v_mov_b32_e32 v52, v125
	v_mov_b32_e32 v51, v125
	v_mov_b32_e32 v50, v125
	v_mov_b32_e32 v41, v125
	v_mov_b32_e32 v40, v125
	v_mov_b32_e32 v39, v125
	v_mov_b32_e32 v38, v125
	v_mov_b32_e32 v37, v125
	v_mov_b32_e32 v36, v125
	v_mov_b32_e32 v35, v125
	v_mov_b32_e32 v34, v125
	v_mov_b32_e32 v25, v125
	v_mov_b32_e32 v24, v125
	v_mov_b32_e32 v23, v125
	v_mov_b32_e32 v22, v125
	v_mov_b32_e32 v21, v125
	v_mov_b32_e32 v20, v125
	v_mov_b32_e32 v19, v125
	v_mov_b32_e32 v18, v125
	v_mov_b32_e32 v9, v125
	v_mov_b32_e32 v8, v125
	v_mov_b32_e32 v7, v125
	v_mov_b32_e32 v6, v125
	v_mov_b32_e32 v5, v125
	v_mov_b32_e32 v4, v125
	v_mov_b32_e32 v3, v125
	v_mov_b32_e32 v2, v125
	s_cbranch_vccnz .LBB0_48
	s_add_u32 s16, s16, 0x80
	s_addc_u32 s17, s17, 0
	s_add_u32 s42, s18, 0x100
	s_addc_u32 s43, s19, 0
	s_mov_b32 s18, 0

; template <class Epi>
; __device__ __forceinline__ void gemm_phase(LAS unsigned char* lds, const Gemm g, const StaticOrder& S, const Epi& E) {
;     ...
;         const bool has_next = S.next(ui + 1, nxt);
;         const char* nA = has_next ? (const char*)g.A + (size_t)nxt.pm * tstep : cA; const char* nB = has_next ? (const char*)g.Bt + (size_t)nxt.pn * tstep : cB;
;         for (int t = 0; t < nt; t += 2) {
;             const bool last = (t == nt - 2);
;             const char* a1 = cA + (size_t)(t + 1) * kstep;
;             const char* a2 = last ? nA : cA + (size_t)(t + 2) * kstep; const char* b2 = last ? nB : cB + (size_t)(t + 2) * kstep;
;     ...
; #pragma unroll
;         for (int a = 0; a < 2; ++a)
; #pragma unroll
;             for (int b = 0; b < 2; ++b)
; #pragma unroll
;                 for (int m = 0; m < 4; ++m)
; #pragma unroll
;                     for (int n = 0; n < 2; ++n) acc[a][b][m][n] = (f32x4){0.f, 0.f, 0.f, 0.f};
;         cur = nxt; cA = nA; cB = nB; ++ui;
.LBB0_611:
	v_mov_b32_e32 v129, 0
	s_andn2_b64 vcc, exec, s[50:51]
	v_mov_b32_e32 v128, v129
	v_mov_b32_e32 v127, v129
	v_mov_b32_e32 v126, v129
	v_mov_b32_e32 v113, v129
	v_mov_b32_e32 v112, v129
	v_mov_b32_e32 v111, v129
	v_mov_b32_e32 v110, v129
	v_mov_b32_e32 v125, v129
	v_mov_b32_e32 v124, v129
	v_mov_b32_e32 v123, v129
	v_mov_b32_e32 v122, v129
	v_mov_b32_e32 v109, v129
	v_mov_b32_e32 v108, v129
	v_mov_b32_e32 v107, v129
	v_mov_b32_e32 v106, v129
	v_mov_b32_e32 v121, v129
	v_mov_b32_e32 v120, v129
	v_mov_b32_e32 v119, v129
	v_mov_b32_e32 v118, v129
	v_mov_b32_e32 v105, v129
	v_mov_b32_e32 v104, v129
	v_mov_b32_e32 v103, v129
	v_mov_b32_e32 v102, v129
	v_mov_b32_e32 v117, v129
	v_mov_b32_e32 v116, v129
	v_mov_b32_e32 v115, v129
	v_mov_b32_e32 v114, v129
	v_mov_b32_e32 v101, v129
	v_mov_b32_e32 v100, v129
	v_mov_b32_e32 v99, v129
	v_mov_b32_e32 v98, v129
	v_mov_b32_e32 v97, v129
	v_mov_b32_e32 v96, v129
	v_mov_b32_e32 v95, v129
	v_mov_b32_e32 v94, v129
	v_mov_b32_e32 v81, v129
	v_mov_b32_e32 v80, v129
	v_mov_b32_e32 v79, v129
	v_mov_b32_e32 v78, v129
	v_mov_b32_e32 v93, v129
	v_mov_b32_e32 v92, v129
	v_mov_b32_e32 v91, v129
	v_mov_b32_e32 v90, v129
	v_mov_b32_e32 v77, v129
	v_mov_b32_e32 v76, v129
	v_mov_b32_e32 v75, v129
	v_mov_b32_e32 v74, v129
	v_mov_b32_e32 v89, v129
	v_mov_b32_e32 v88, v129
	v_mov_b32_e32 v87, v129
	v_mov_b32_e32 v86, v129
	v_mov_b32_e32 v73, v129
	v_mov_b32_e32 v72, v129
	s_waitcnt vmcnt(0)
	v_mov_b32_e32 v71, v129
	v_mov_b32_e32 v70, v129
	v_mov_b32_e32 v85, v129
	v_mov_b32_e32 v84, v129
	v_mov_b32_e32 v83, v129
	v_mov_b32_e32 v82, v129
	v_mov_b32_e32 v69, v129
	v_mov_b32_e32 v68, v129
	v_mov_b32_e32 v67, v129
	v_mov_b32_e32 v66, v129
	v_mov_b32_e32 v65, v129
	v_mov_b32_e32 v64, v129
	v_mov_b32_e32 v63, v129
	v_mov_b32_e32 v62, v129
	v_mov_b32_e32 v49, v129
	v_mov_b32_e32 v48, v129
	v_mov_b32_e32 v47, v129
	v_mov_b32_e32 v46, v129
	v_mov_b32_e32 v61, v129
	v_mov_b32_e32 v60, v129
	v_mov_b32_e32 v59, v129
	v_mov_b32_e32 v58, v129
	v_mov_b32_e32 v45, v129
	v_mov_b32_e32 v44, v129
	v_mov_b32_e32 v43, v129
	v_mov_b32_e32 v42, v129
	v_mov_b32_e32 v57, v129
	v_mov_b32_e32 v56, v129
	v_mov_b32_e32 v55, v129
	v_mov_b32_e32 v54, v129
	v_mov_b32_e32 v41, v129
	v_mov_b32_e32 v40, v129
	v_mov_b32_e32 v39, v129
	v_mov_b32_e32 v38, v129
	v_mov_b32_e32 v53, v129
	v_mov_b32_e32 v52, v129
	v_mov_b32_e32 v51, v129
	v_mov_b32_e32 v50, v129
	v_mov_b32_e32 v37, v129
	v_mov_b32_e32 v36, v129
	v_mov_b32_e32 v35, v129
	v_mov_b32_e32 v34, v129
	v_mov_b32_e32 v33, v129
	v_mov_b32_e32 v32, v129
	v_mov_b32_e32 v31, v129
	v_mov_b32_e32 v30, v129
	v_mov_b32_e32 v17, v129
	v_mov_b32_e32 v16, v129
	v_mov_b32_e32 v15, v129
	v_mov_b32_e32 v14, v129
	v_mov_b32_e32 v29, v129
	v_mov_b32_e32 v28, v129
	v_mov_b32_e32 v27, v129
	v_mov_b32_e32 v26, v129
	v_mov_b32_e32 v13, v129
	v_mov_b32_e32 v12, v129
	v_mov_b32_e32 v11, v129
	v_mov_b32_e32 v10, v129
	v_mov_b32_e32 v25, v129
	v_mov_b32_e32 v24, v129
	v_mov_b32_e32 v23, v129
	v_mov_b32_e32 v22, v129
	v_mov_b32_e32 v9, v129
	v_mov_b32_e32 v8, v129
	v_mov_b32_e32 v7, v129
	v_mov_b32_e32 v6, v129
	v_mov_b32_e32 v21, v129
	v_mov_b32_e32 v20, v129
	v_mov_b32_e32 v19, v129
	v_mov_b32_e32 v18, v129
	v_mov_b32_e32 v5, v129
	v_mov_b32_e32 v4, v129
	v_mov_b32_e32 v3, v129
	v_mov_b32_e32 v2, v129
	s_cbranch_vccnz .LBB0_614
	s_add_u32 s2, s2, 0x80
	s_addc_u32 s3, s3, 0
	s_add_u32 s26, s4, 0x100
	s_addc_u32 s28, s5, 0
	s_mov_b32 s4, 0

; template <class Epi>
; __device__ __forceinline__ void gemm_phase(LAS unsigned char* lds, const Gemm g, const StaticOrder& S, const Epi& E) {
;     ...
;         const bool has_next = S.next(ui + 1, nxt);
;         const char* nA = has_next ? (const char*)g.A + (size_t)nxt.pm * tstep : cA; const char* nB = has_next ? (const char*)g.Bt + (size_t)nxt.pn * tstep : cB;
;         for (int t = 0; t < nt; t += 2) {
;             const bool last = (t == nt - 2);
;             const char* a1 = cA + (size_t)(t + 1) * kstep;
;             const char* a2 = last ? nA : cA + (size_t)(t + 2) * kstep; const char* b2 = last ? nB : cB + (size_t)(t + 2) * kstep;
;     ...
; #pragma unroll
;         for (int a = 0; a < 2; ++a)
; #pragma unroll
;             for (int b = 0; b < 2; ++b)
; #pragma unroll
;                 for (int m = 0; m < 4; ++m)
; #pragma unroll
;                     for (int n = 0; n < 2; ++n) acc[a][b][m][n] = (f32x4){0.f, 0.f, 0.f, 0.f};
;         cur = nxt; cA = nA; cB = nB; ++ui;
.LBB0_749:
	v_mov_b32_e32 v125, 0
	s_andn2_b64 vcc, exec, s[8:9]
	v_mov_b32_e32 v124, v125
	v_mov_b32_e32 v123, v125
	v_mov_b32_e32 v122, v125
	v_mov_b32_e32 v129, v125
	v_mov_b32_e32 v128, v125
	v_mov_b32_e32 v127, v125
	v_mov_b32_e32 v126, v125
	v_mov_b32_e32 v113, v125
	v_mov_b32_e32 v112, v125
	v_mov_b32_e32 v111, v125
	v_mov_b32_e32 v110, v125
	v_mov_b32_e32 v109, v125
	v_mov_b32_e32 v108, v125
	v_mov_b32_e32 v107, v125
	v_mov_b32_e32 v106, v125
	v_mov_b32_e32 v97, v125
	v_mov_b32_e32 v96, v125
	v_mov_b32_e32 v95, v125
	v_mov_b32_e32 v94, v125
	v_mov_b32_e32 v93, v125
	v_mov_b32_e32 v92, v125
	v_mov_b32_e32 v91, v125
	v_mov_b32_e32 v90, v125
	v_mov_b32_e32 v81, v125
	v_mov_b32_e32 v80, v125
	v_mov_b32_e32 v79, v125
	v_mov_b32_e32 v78, v125
	v_mov_b32_e32 v77, v125
	v_mov_b32_e32 v76, v125
	v_mov_b32_e32 v75, v125
	v_mov_b32_e32 v74, v125
	v_mov_b32_e32 v121, v125
	v_mov_b32_e32 v120, v125
	v_mov_b32_e32 v119, v125
	v_mov_b32_e32 v118, v125
	v_mov_b32_e32 v117, v125
	v_mov_b32_e32 v116, v125
	v_mov_b32_e32 v115, v125
	v_mov_b32_e32 v114, v125
	v_mov_b32_e32 v105, v125
	v_mov_b32_e32 v104, v125
	v_mov_b32_e32 v103, v125
	v_mov_b32_e32 v102, v125
	v_mov_b32_e32 v101, v125
	v_mov_b32_e32 v100, v125
	v_mov_b32_e32 v99, v125
	v_mov_b32_e32 v98, v125
	v_mov_b32_e32 v89, v125
	v_mov_b32_e32 v88, v125
	v_mov_b32_e32 v87, v125
	v_mov_b32_e32 v86, v125
	v_mov_b32_e32 v85, v125
	v_mov_b32_e32 v84, v125
	v_mov_b32_e32 v83, v125
	v_mov_b32_e32 v82, v125
	v_mov_b32_e32 v73, v125
	v_mov_b32_e32 v72, v125
	v_mov_b32_e32 v71, v125
	v_mov_b32_e32 v70, v125
	v_mov_b32_e32 v69, v125
	v_mov_b32_e32 v68, v125
	v_mov_b32_e32 v67, v125
	v_mov_b32_e32 v66, v125
	v_mov_b32_e32 v65, v125
	v_mov_b32_e32 v64, v125
	v_mov_b32_e32 v63, v125
	v_mov_b32_e32 v62, v125
	v_mov_b32_e32 v61, v125
	v_mov_b32_e32 v60, v125
	v_mov_b32_e32 v59, v125
	v_mov_b32_e32 v58, v125
	v_mov_b32_e32 v49, v125
	v_mov_b32_e32 v48, v125
	v_mov_b32_e32 v47, v125
	v_mov_b32_e32 v46, v125
	v_mov_b32_e32 v45, v125
	v_mov_b32_e32 v44, v125
	v_mov_b32_e32 v43, v125
	v_mov_b32_e32 v42, v125
	v_mov_b32_e32 v33, v125
	v_mov_b32_e32 v32, v125
	v_mov_b32_e32 v31, v125
	v_mov_b32_e32 v30, v125
	v_mov_b32_e32 v29, v125
	v_mov_b32_e32 v28, v125
	v_mov_b32_e32 v27, v125
	v_mov_b32_e32 v26, v125
	v_mov_b32_e32 v17, v125
	v_mov_b32_e32 v16, v125
	v_mov_b32_e32 v15, v125
	v_mov_b32_e32 v14, v125
	v_mov_b32_e32 v13, v125
	v_mov_b32_e32 v12, v125
	v_mov_b32_e32 v11, v125
	v_mov_b32_e32 v10, v125
	v_mov_b32_e32 v57, v125
	v_mov_b32_e32 v56, v125
	v_mov_b32_e32 v55, v125
	v_mov_b32_e32 v54, v125
	v_mov_b32_e32 v53, v125
	v_mov_b32_e32 v52, v125
	v_mov_b32_e32 v51, v125
	v_mov_b32_e32 v50, v125
	v_mov_b32_e32 v41, v125
	v_mov_b32_e32 v40, v125
	v_mov_b32_e32 v39, v125
	v_mov_b32_e32 v38, v125
	v_mov_b32_e32 v37, v125
	v_mov_b32_e32 v36, v125
	v_mov_b32_e32 v35, v125
	v_mov_b32_e32 v34, v125
	v_mov_b32_e32 v25, v125
	v_mov_b32_e32 v24, v125
	v_mov_b32_e32 v23, v125
	v_mov_b32_e32 v22, v125
	v_mov_b32_e32 v21, v125
	v_mov_b32_e32 v20, v125
	v_mov_b32_e32 v19, v125
	v_mov_b32_e32 v18, v125
	v_mov_b32_e32 v9, v125
	v_mov_b32_e32 v8, v125
	v_mov_b32_e32 v7, v125
	v_mov_b32_e32 v6, v125
	v_mov_b32_e32 v5, v125
	v_mov_b32_e32 v4, v125
	v_mov_b32_e32 v3, v125
	v_mov_b32_e32 v2, v125
	s_cbranch_vccnz .LBB0_738
	s_add_u32 s14, s14, 0x80
	s_addc_u32 s15, s15, 0
	s_add_u32 s42, s16, 0x100
	s_addc_u32 s43, s17, 0
	s_mov_b32 s16, 0

; template <class Epi>
; __device__ __forceinline__ void gemm_phase(LAS unsigned char* lds, const Gemm g, const StaticOrder& S, const Epi& E) {
;     ...
;         const bool has_next = S.next(ui + 1, nxt);
;         const char* nA = has_next ? (const char*)g.A + (size_t)nxt.pm * tstep : cA; const char* nB = has_next ? (const char*)g.Bt + (size_t)nxt.pn * tstep : cB;
;         for (int t = 0; t < nt; t += 2) {
;             const bool last = (t == nt - 2);
;             const char* a1 = cA + (size_t)(t + 1) * kstep;
;             const char* a2 = last ? nA : cA + (size_t)(t + 2) * kstep; const char* b2 = last ? nB : cB + (size_t)(t + 2) * kstep;
;     ...
; #pragma unroll
;         for (int a = 0; a < 2; ++a)
; #pragma unroll
;             for (int b = 0; b < 2; ++b)
; #pragma unroll
;                 for (int m = 0; m < 4; ++m)
; #pragma unroll
;                     for (int n = 0; n < 2; ++n) acc[a][b][m][n] = (f32x4){0.f, 0.f, 0.f, 0.f};
;         cur = nxt; cA = nA; cB = nB; ++ui;
.LBB0_777:
	v_mov_b32_e32 v125, 0
	s_andn2_b64 vcc, exec, s[46:47]
	v_mov_b32_e32 v124, v125
	v_mov_b32_e32 v123, v125
	v_mov_b32_e32 v122, v125
	v_mov_b32_e32 v117, v125
	v_mov_b32_e32 v116, v125
	v_mov_b32_e32 v115, v125
	v_mov_b32_e32 v114, v125
	v_mov_b32_e32 v129, v125
	v_mov_b32_e32 v128, v125
	v_mov_b32_e32 v127, v125
	v_mov_b32_e32 v126, v125
	v_mov_b32_e32 v121, v125
	v_mov_b32_e32 v120, v125
	v_mov_b32_e32 v119, v125
	v_mov_b32_e32 v118, v125
	v_mov_b32_e32 v97, v125
	v_mov_b32_e32 v96, v125
	v_mov_b32_e32 v95, v125
	v_mov_b32_e32 v94, v125
	v_mov_b32_e32 v93, v125
	v_mov_b32_e32 v92, v125
	v_mov_b32_e32 v91, v125
	v_mov_b32_e32 v90, v125
	v_mov_b32_e32 v81, v125
	v_mov_b32_e32 v80, v125
	v_mov_b32_e32 v79, v125
	v_mov_b32_e32 v78, v125
	v_mov_b32_e32 v77, v125
	v_mov_b32_e32 v76, v125
	v_mov_b32_e32 v75, v125
	v_mov_b32_e32 v74, v125
	v_mov_b32_e32 v113, v125
	v_mov_b32_e32 v112, v125
	v_mov_b32_e32 v111, v125
	v_mov_b32_e32 v110, v125
	v_mov_b32_e32 v109, v125
	v_mov_b32_e32 v108, v125
	v_mov_b32_e32 v107, v125
	v_mov_b32_e32 v106, v125
	v_mov_b32_e32 v105, v125
	v_mov_b32_e32 v104, v125
	v_mov_b32_e32 v103, v125
	v_mov_b32_e32 v102, v125
	v_mov_b32_e32 v101, v125
	v_mov_b32_e32 v100, v125
	v_mov_b32_e32 v99, v125
	v_mov_b32_e32 v98, v125
	v_mov_b32_e32 v89, v125
	v_mov_b32_e32 v88, v125
	v_mov_b32_e32 v87, v125
	v_mov_b32_e32 v86, v125
	v_mov_b32_e32 v85, v125
	v_mov_b32_e32 v84, v125
	v_mov_b32_e32 v83, v125
	v_mov_b32_e32 v82, v125
	v_mov_b32_e32 v73, v125
	v_mov_b32_e32 v72, v125
	v_mov_b32_e32 v71, v125
	v_mov_b32_e32 v70, v125
	v_mov_b32_e32 v69, v125
	v_mov_b32_e32 v68, v125
	v_mov_b32_e32 v67, v125
	v_mov_b32_e32 v66, v125
	v_mov_b32_e32 v65, v125
	v_mov_b32_e32 v64, v125
	v_mov_b32_e32 v63, v125
	v_mov_b32_e32 v62, v125
	v_mov_b32_e32 v61, v125
	v_mov_b32_e32 v60, v125
	v_mov_b32_e32 v59, v125
	v_mov_b32_e32 v58, v125
	v_mov_b32_e32 v49, v125
	v_mov_b32_e32 v48, v125
	v_mov_b32_e32 v47, v125
	v_mov_b32_e32 v46, v125
	v_mov_b32_e32 v45, v125
	v_mov_b32_e32 v44, v125
	v_mov_b32_e32 v43, v125
	v_mov_b32_e32 v42, v125
	v_mov_b32_e32 v33, v125
	v_mov_b32_e32 v32, v125
	v_mov_b32_e32 v31, v125
	v_mov_b32_e32 v30, v125
	v_mov_b32_e32 v29, v125
	v_mov_b32_e32 v28, v125
	v_mov_b32_e32 v27, v125
	v_mov_b32_e32 v26, v125
	v_mov_b32_e32 v17, v125
	v_mov_b32_e32 v16, v125
	v_mov_b32_e32 v15, v125
	v_mov_b32_e32 v14, v125
	v_mov_b32_e32 v13, v125
	v_mov_b32_e32 v12, v125
	v_mov_b32_e32 v11, v125
	v_mov_b32_e32 v10, v125
	v_mov_b32_e32 v57, v125
	v_mov_b32_e32 v56, v125
	v_mov_b32_e32 v55, v125
	v_mov_b32_e32 v54, v125
	v_mov_b32_e32 v53, v125
	v_mov_b32_e32 v52, v125
	v_mov_b32_e32 v51, v125
	v_mov_b32_e32 v50, v125
	v_mov_b32_e32 v41, v125
	v_mov_b32_e32 v40, v125
	v_mov_b32_e32 v39, v125
	v_mov_b32_e32 v38, v125
	v_mov_b32_e32 v37, v125
	v_mov_b32_e32 v36, v125
	v_mov_b32_e32 v35, v125
	v_mov_b32_e32 v34, v125
	v_mov_b32_e32 v25, v125
	v_mov_b32_e32 v24, v125
	v_mov_b32_e32 v23, v125
	v_mov_b32_e32 v22, v125
	v_mov_b32_e32 v21, v125
	v_mov_b32_e32 v20, v125
	v_mov_b32_e32 v19, v125
	v_mov_b32_e32 v18, v125
	v_mov_b32_e32 v9, v125
	v_mov_b32_e32 v8, v125
	v_mov_b32_e32 v7, v125
	v_mov_b32_e32 v6, v125
	v_mov_b32_e32 v5, v125
	v_mov_b32_e32 v4, v125
	v_mov_b32_e32 v3, v125
	v_mov_b32_e32 v2, v125
	s_cbranch_vccnz .LBB0_781
	s_add_u32 s2, s2, 0x80
	s_addc_u32 s3, s3, 0
	s_add_u32 s28, s4, 0x100
	s_addc_u32 s42, s5, 0
	s_mov_b32 s4, 0

; template <class Epi>
; __device__ __forceinline__ void gemm_phase(LAS unsigned char* lds, const Gemm g, const StaticOrder& S, const Epi& E) {
;     ...
;         const bool has_next = S.next(ui + 1, nxt);
;         const char* nA = has_next ? (const char*)g.A + (size_t)nxt.pm * tstep : cA; const char* nB = has_next ? (const char*)g.Bt + (size_t)nxt.pn * tstep : cB;
;         for (int t = 0; t < nt; t += 2) {
;             const bool last = (t == nt - 2);
;             const char* a1 = cA + (size_t)(t + 1) * kstep;
;             const char* a2 = last ? nA : cA + (size_t)(t + 2) * kstep; const char* b2 = last ? nB : cB + (size_t)(t + 2) * kstep;
;     ...
; #pragma unroll
;         for (int a = 0; a < 2; ++a)
; #pragma unroll
;             for (int b = 0; b < 2; ++b)
; #pragma unroll
;                 for (int m = 0; m < 4; ++m)
; #pragma unroll
;                     for (int n = 0; n < 2; ++n) acc[a][b][m][n] = (f32x4){0.f, 0.f, 0.f, 0.f};
;         cur = nxt; cA = nA; cB = nB; ++ui;
.LBB0_847:
	v_mov_b32_e32 v125, 0
	s_andn2_b64 vcc, exec, s[10:11]
	v_mov_b32_e32 v124, v125
	v_mov_b32_e32 v123, v125
	v_mov_b32_e32 v122, v125
	v_mov_b32_e32 v129, v125
	v_mov_b32_e32 v128, v125
	v_mov_b32_e32 v127, v125
	v_mov_b32_e32 v126, v125
	v_mov_b32_e32 v113, v125
	v_mov_b32_e32 v112, v125
	v_mov_b32_e32 v111, v125
	v_mov_b32_e32 v110, v125
	v_mov_b32_e32 v109, v125
	v_mov_b32_e32 v108, v125
	v_mov_b32_e32 v107, v125
	v_mov_b32_e32 v106, v125
	v_mov_b32_e32 v97, v125
	v_mov_b32_e32 v96, v125
	v_mov_b32_e32 v95, v125
	v_mov_b32_e32 v94, v125
	v_mov_b32_e32 v93, v125
	v_mov_b32_e32 v92, v125
	v_mov_b32_e32 v91, v125
	v_mov_b32_e32 v90, v125
	v_mov_b32_e32 v81, v125
	v_mov_b32_e32 v80, v125
	v_mov_b32_e32 v79, v125
	v_mov_b32_e32 v78, v125
	v_mov_b32_e32 v77, v125
	v_mov_b32_e32 v76, v125
	v_mov_b32_e32 v75, v125
	v_mov_b32_e32 v74, v125
	v_mov_b32_e32 v121, v125
	v_mov_b32_e32 v120, v125
	v_mov_b32_e32 v119, v125
	v_mov_b32_e32 v118, v125
	v_mov_b32_e32 v117, v125
	v_mov_b32_e32 v116, v125
	v_mov_b32_e32 v115, v125
	v_mov_b32_e32 v114, v125
	v_mov_b32_e32 v105, v125
	v_mov_b32_e32 v104, v125
	v_mov_b32_e32 v103, v125
	v_mov_b32_e32 v102, v125
	v_mov_b32_e32 v101, v125
	v_mov_b32_e32 v100, v125
	v_mov_b32_e32 v99, v125
	v_mov_b32_e32 v98, v125
	v_mov_b32_e32 v89, v125
	v_mov_b32_e32 v88, v125
	v_mov_b32_e32 v87, v125
	v_mov_b32_e32 v86, v125
	v_mov_b32_e32 v85, v125
	v_mov_b32_e32 v84, v125
	v_mov_b32_e32 v83, v125
	v_mov_b32_e32 v82, v125
	v_mov_b32_e32 v73, v125
	v_mov_b32_e32 v72, v125
	s_waitcnt vmcnt(0)
	v_mov_b32_e32 v71, v125
	v_mov_b32_e32 v70, v125
	v_mov_b32_e32 v69, v125
	v_mov_b32_e32 v68, v125
	v_mov_b32_e32 v67, v125
	v_mov_b32_e32 v66, v125
	v_mov_b32_e32 v65, v125
	v_mov_b32_e32 v64, v125
	v_mov_b32_e32 v63, v125
	v_mov_b32_e32 v62, v125
	v_mov_b32_e32 v61, v125
	v_mov_b32_e32 v60, v125
	v_mov_b32_e32 v59, v125
	v_mov_b32_e32 v58, v125
	v_mov_b32_e32 v49, v125
	v_mov_b32_e32 v48, v125
	v_mov_b32_e32 v47, v125
	v_mov_b32_e32 v46, v125
	v_mov_b32_e32 v45, v125
	v_mov_b32_e32 v44, v125
	v_mov_b32_e32 v43, v125
	v_mov_b32_e32 v42, v125
	v_mov_b32_e32 v33, v125
	v_mov_b32_e32 v32, v125
	v_mov_b32_e32 v31, v125
	v_mov_b32_e32 v30, v125
	v_mov_b32_e32 v29, v125
	v_mov_b32_e32 v28, v125
	v_mov_b32_e32 v27, v125
	v_mov_b32_e32 v26, v125
	v_mov_b32_e32 v17, v125
	v_mov_b32_e32 v16, v125
	v_mov_b32_e32 v15, v125
	v_mov_b32_e32 v14, v125
	v_mov_b32_e32 v13, v125
	v_mov_b32_e32 v12, v125
	v_mov_b32_e32 v11, v125
	v_mov_b32_e32 v10, v125
	v_mov_b32_e32 v57, v125
	v_mov_b32_e32 v56, v125
	v_mov_b32_e32 v55, v125
	v_mov_b32_e32 v54, v125
	v_mov_b32_e32 v53, v125
	v_mov_b32_e32 v52, v125
	v_mov_b32_e32 v51, v125
	v_mov_b32_e32 v50, v125
	v_mov_b32_e32 v41, v125
	v_mov_b32_e32 v40, v125
	v_mov_b32_e32 v39, v125
	v_mov_b32_e32 v38, v125
	v_mov_b32_e32 v37, v125
	v_mov_b32_e32 v36, v125
	v_mov_b32_e32 v35, v125
	v_mov_b32_e32 v34, v125
	v_mov_b32_e32 v25, v125
	v_mov_b32_e32 v24, v125
	v_mov_b32_e32 v23, v125
	v_mov_b32_e32 v22, v125
	v_mov_b32_e32 v21, v125
	v_mov_b32_e32 v20, v125
	v_mov_b32_e32 v19, v125
	v_mov_b32_e32 v18, v125
	v_mov_b32_e32 v9, v125
	v_mov_b32_e32 v8, v125
	v_mov_b32_e32 v7, v125
	v_mov_b32_e32 v6, v125
	v_mov_b32_e32 v5, v125
	v_mov_b32_e32 v4, v125
	v_mov_b32_e32 v3, v125
	v_mov_b32_e32 v2, v125
	s_cbranch_vccnz .LBB0_851
	s_add_u32 s16, s16, 0x80
	s_addc_u32 s17, s17, 0
	s_add_u32 s42, s18, 0x100
	s_addc_u32 s43, s19, 0
	s_mov_b32 s18, 0

; template <class Epi>
; __device__ __forceinline__ void gemm_phase(LAS unsigned char* lds, const Gemm g, const StaticOrder& S, const Epi& E) {
;     ...
;         const bool has_next = S.next(ui + 1, nxt);
;         const char* nA = has_next ? (const char*)g.A + (size_t)nxt.pm * tstep : cA; const char* nB = has_next ? (const char*)g.Bt + (size_t)nxt.pn * tstep : cB;
;         for (int t = 0; t < nt; t += 2) {
;             const bool last = (t == nt - 2);
;             const char* a1 = cA + (size_t)(t + 1) * kstep;
;             const char* a2 = last ? nA : cA + (size_t)(t + 2) * kstep; const char* b2 = last ? nB : cB + (size_t)(t + 2) * kstep;
;     ...
; #pragma unroll
;         for (int a = 0; a < 2; ++a)
; #pragma unroll
;             for (int b = 0; b < 2; ++b)
; #pragma unroll
;                 for (int m = 0; m < 4; ++m)
; #pragma unroll
;                     for (int n = 0; n < 2; ++n) acc[a][b][m][n] = (f32x4){0.f, 0.f, 0.f, 0.f};
;         cur = nxt; cA = nA; cB = nB; ++ui;
.LBB0_886:
	v_readlane_b32 s42, v255, 27
	v_mov_b32_e32 v125, 0
	v_readlane_b32 s43, v255, 28
	s_andn2_b64 vcc, exec, s[42:43]
	v_mov_b32_e32 v124, v125
	v_mov_b32_e32 v123, v125
	v_mov_b32_e32 v122, v125
	v_mov_b32_e32 v97, v125
	v_mov_b32_e32 v96, v125
	v_mov_b32_e32 v95, v125
	v_mov_b32_e32 v94, v125
	v_mov_b32_e32 v121, v125
	v_mov_b32_e32 v120, v125
	v_mov_b32_e32 v119, v125
	v_mov_b32_e32 v118, v125
	v_mov_b32_e32 v89, v125
	v_mov_b32_e32 v88, v125
	v_mov_b32_e32 v87, v125
	v_mov_b32_e32 v86, v125
	v_mov_b32_e32 v113, v125
	v_mov_b32_e32 v112, v125
	v_mov_b32_e32 v111, v125
	v_mov_b32_e32 v110, v125
	v_mov_b32_e32 v81, v125
	v_mov_b32_e32 v80, v125
	v_mov_b32_e32 v79, v125
	v_mov_b32_e32 v78, v125
	v_mov_b32_e32 v105, v125
	v_mov_b32_e32 v104, v125
	v_mov_b32_e32 v103, v125
	v_mov_b32_e32 v102, v125
	v_mov_b32_e32 v73, v125
	v_mov_b32_e32 v72, v125
	s_waitcnt vmcnt(0)
	v_mov_b32_e32 v71, v125
	v_mov_b32_e32 v70, v125
	v_mov_b32_e32 v129, v125
	v_mov_b32_e32 v128, v125
	v_mov_b32_e32 v127, v125
	v_mov_b32_e32 v126, v125
	v_mov_b32_e32 v93, v125
	v_mov_b32_e32 v92, v125
	v_mov_b32_e32 v91, v125
	v_mov_b32_e32 v90, v125
	v_mov_b32_e32 v117, v125
	v_mov_b32_e32 v116, v125
	v_mov_b32_e32 v115, v125
	v_mov_b32_e32 v114, v125
	v_mov_b32_e32 v85, v125
	v_mov_b32_e32 v84, v125
	v_mov_b32_e32 v83, v125
	v_mov_b32_e32 v82, v125
	v_mov_b32_e32 v109, v125
	v_mov_b32_e32 v108, v125
	v_mov_b32_e32 v107, v125
	v_mov_b32_e32 v106, v125
	v_mov_b32_e32 v77, v125
	v_mov_b32_e32 v76, v125
	v_mov_b32_e32 v75, v125
	v_mov_b32_e32 v74, v125
	v_mov_b32_e32 v101, v125
	v_mov_b32_e32 v100, v125
	v_mov_b32_e32 v99, v125
	v_mov_b32_e32 v98, v125
	v_mov_b32_e32 v69, v125
	v_mov_b32_e32 v68, v125
	v_mov_b32_e32 v67, v125
	v_mov_b32_e32 v66, v125
	v_mov_b32_e32 v65, v125
	v_mov_b32_e32 v64, v125
	v_mov_b32_e32 v63, v125
	v_mov_b32_e32 v62, v125
	v_mov_b32_e32 v33, v125
	v_mov_b32_e32 v32, v125
	v_mov_b32_e32 v31, v125
	v_mov_b32_e32 v30, v125
	v_mov_b32_e32 v57, v125
	v_mov_b32_e32 v56, v125
	v_mov_b32_e32 v55, v125
	v_mov_b32_e32 v54, v125
	v_mov_b32_e32 v29, v125
	v_mov_b32_e32 v28, v125
	v_mov_b32_e32 v27, v125
	v_mov_b32_e32 v26, v125
	v_mov_b32_e32 v49, v125
	v_mov_b32_e32 v48, v125
	v_mov_b32_e32 v47, v125
	v_mov_b32_e32 v46, v125
	v_mov_b32_e32 v17, v125
	v_mov_b32_e32 v16, v125
	v_mov_b32_e32 v15, v125
	v_mov_b32_e32 v14, v125
	v_mov_b32_e32 v41, v125
	v_mov_b32_e32 v40, v125
	v_mov_b32_e32 v39, v125
	v_mov_b32_e32 v38, v125
	v_mov_b32_e32 v9, v125
	v_mov_b32_e32 v8, v125
	v_mov_b32_e32 v7, v125
	v_mov_b32_e32 v6, v125
	v_mov_b32_e32 v61, v125
	v_mov_b32_e32 v60, v125
	v_mov_b32_e32 v59, v125
	v_mov_b32_e32 v58, v125
	v_mov_b32_e32 v25, v125
	v_mov_b32_e32 v24, v125
	v_mov_b32_e32 v23, v125
	v_mov_b32_e32 v22, v125
	v_mov_b32_e32 v53, v125
	v_mov_b32_e32 v52, v125
	v_mov_b32_e32 v51, v125
	v_mov_b32_e32 v50, v125
	v_mov_b32_e32 v21, v125
	v_mov_b32_e32 v20, v125
	v_mov_b32_e32 v19, v125
	v_mov_b32_e32 v18, v125
	v_mov_b32_e32 v45, v125
	v_mov_b32_e32 v44, v125
	v_mov_b32_e32 v43, v125
	v_mov_b32_e32 v42, v125
	v_mov_b32_e32 v13, v125
	v_mov_b32_e32 v12, v125
	v_mov_b32_e32 v11, v125
	v_mov_b32_e32 v10, v125
	v_mov_b32_e32 v37, v125
	v_mov_b32_e32 v36, v125
	v_mov_b32_e32 v35, v125
	v_mov_b32_e32 v34, v125
	v_mov_b32_e32 v5, v125
	v_mov_b32_e32 v4, v125
	v_mov_b32_e32 v3, v125
	v_mov_b32_e32 v2, v125
	s_cbranch_vccnz .LBB0_889
	s_add_u32 s50, s36, 0x100
	s_addc_u32 s51, s37, 0
	s_add_u32 s36, s46, 0x80
	s_addc_u32 s37, s47, 0
	s_mov_b32 s42, 0

; template <class Epi>
; __device__ __forceinline__ void gemm_phase(LAS unsigned char* lds, const Gemm g, const StaticOrder& S, const Epi& E) {
;     ...
;         const bool has_next = S.next(ui + 1, nxt);
;         const char* nA = has_next ? (const char*)g.A + (size_t)nxt.pm * tstep : cA; const char* nB = has_next ? (const char*)g.Bt + (size_t)nxt.pn * tstep : cB;
;         for (int t = 0; t < nt; t += 2) {
;             const bool last = (t == nt - 2);
;             const char* a1 = cA + (size_t)(t + 1) * kstep;
;             const char* a2 = last ? nA : cA + (size_t)(t + 2) * kstep; const char* b2 = last ? nB : cB + (size_t)(t + 2) * kstep;
;     ...
; #pragma unroll
;         for (int a = 0; a < 2; ++a)
; #pragma unroll
;             for (int b = 0; b < 2; ++b)
; #pragma unroll
;                 for (int m = 0; m < 4; ++m)
; #pragma unroll
;                     for (int n = 0; n < 2; ++n) acc[a][b][m][n] = (f32x4){0.f, 0.f, 0.f, 0.f};
;         cur = nxt; cA = nA; cB = nB; ++ui;
.LBB0_972:
	v_mov_b32_e32 v125, 0
	s_andn2_b64 vcc, exec, s[6:7]
	v_mov_b32_e32 v124, v125
	v_mov_b32_e32 v123, v125
	v_mov_b32_e32 v122, v125
	v_mov_b32_e32 v129, v125
	v_mov_b32_e32 v128, v125
	v_mov_b32_e32 v127, v125
	v_mov_b32_e32 v126, v125
	v_mov_b32_e32 v113, v125
	v_mov_b32_e32 v112, v125
	v_mov_b32_e32 v111, v125
	v_mov_b32_e32 v110, v125
	v_mov_b32_e32 v109, v125
	v_mov_b32_e32 v108, v125
	v_mov_b32_e32 v107, v125
	v_mov_b32_e32 v106, v125
	v_mov_b32_e32 v97, v125
	v_mov_b32_e32 v96, v125
	v_mov_b32_e32 v95, v125
	v_mov_b32_e32 v94, v125
	v_mov_b32_e32 v93, v125
	v_mov_b32_e32 v92, v125
	v_mov_b32_e32 v91, v125
	v_mov_b32_e32 v90, v125
	v_mov_b32_e32 v81, v125
	v_mov_b32_e32 v80, v125
	v_mov_b32_e32 v79, v125
	v_mov_b32_e32 v78, v125
	v_mov_b32_e32 v77, v125
	v_mov_b32_e32 v76, v125
	v_mov_b32_e32 v75, v125
	v_mov_b32_e32 v74, v125
	v_mov_b32_e32 v121, v125
	v_mov_b32_e32 v120, v125
	v_mov_b32_e32 v119, v125
	v_mov_b32_e32 v118, v125
	v_mov_b32_e32 v117, v125
	v_mov_b32_e32 v116, v125
	v_mov_b32_e32 v115, v125
	v_mov_b32_e32 v114, v125
	v_mov_b32_e32 v105, v125
	v_mov_b32_e32 v104, v125
	v_mov_b32_e32 v103, v125
	v_mov_b32_e32 v102, v125
	v_mov_b32_e32 v101, v125
	v_mov_b32_e32 v100, v125
	v_mov_b32_e32 v99, v125
	v_mov_b32_e32 v98, v125
	v_mov_b32_e32 v89, v125
	v_mov_b32_e32 v88, v125
	v_mov_b32_e32 v87, v125
	v_mov_b32_e32 v86, v125
	v_mov_b32_e32 v85, v125
	v_mov_b32_e32 v84, v125
	v_mov_b32_e32 v83, v125
	v_mov_b32_e32 v82, v125
	v_mov_b32_e32 v73, v125
	v_mov_b32_e32 v72, v125
	v_mov_b32_e32 v71, v125
	v_mov_b32_e32 v70, v125
	v_mov_b32_e32 v69, v125
	v_mov_b32_e32 v68, v125
	v_mov_b32_e32 v67, v125
	v_mov_b32_e32 v66, v125
	v_mov_b32_e32 v65, v125
	v_mov_b32_e32 v64, v125
	v_mov_b32_e32 v63, v125
	v_mov_b32_e32 v62, v125
	v_mov_b32_e32 v61, v125
	v_mov_b32_e32 v60, v125
	v_mov_b32_e32 v59, v125
	v_mov_b32_e32 v58, v125
	v_mov_b32_e32 v49, v125
	v_mov_b32_e32 v48, v125
	v_mov_b32_e32 v47, v125
	v_mov_b32_e32 v46, v125
	v_mov_b32_e32 v45, v125
	v_mov_b32_e32 v44, v125
	v_mov_b32_e32 v43, v125
	v_mov_b32_e32 v42, v125
	v_mov_b32_e32 v33, v125
	v_mov_b32_e32 v32, v125
	v_mov_b32_e32 v31, v125
	v_mov_b32_e32 v30, v125
	v_mov_b32_e32 v29, v125
	v_mov_b32_e32 v28, v125
	v_mov_b32_e32 v27, v125
	v_mov_b32_e32 v26, v125
	v_mov_b32_e32 v17, v125
	v_mov_b32_e32 v16, v125
	v_mov_b32_e32 v15, v125
	v_mov_b32_e32 v14, v125
	v_mov_b32_e32 v13, v125
	v_mov_b32_e32 v12, v125
	v_mov_b32_e32 v11, v125
	v_mov_b32_e32 v10, v125
	v_mov_b32_e32 v57, v125
	v_mov_b32_e32 v56, v125
	v_mov_b32_e32 v55, v125
	v_mov_b32_e32 v54, v125
	v_mov_b32_e32 v53, v125
	v_mov_b32_e32 v52, v125
	v_mov_b32_e32 v51, v125
	v_mov_b32_e32 v50, v125
	v_mov_b32_e32 v41, v125
	v_mov_b32_e32 v40, v125
	v_mov_b32_e32 v39, v125
	v_mov_b32_e32 v38, v125
	v_mov_b32_e32 v37, v125
	v_mov_b32_e32 v36, v125
	v_mov_b32_e32 v35, v125
	v_mov_b32_e32 v34, v125
	v_mov_b32_e32 v25, v125
	v_mov_b32_e32 v24, v125
	v_mov_b32_e32 v23, v125
	v_mov_b32_e32 v22, v125
	v_mov_b32_e32 v21, v125
	v_mov_b32_e32 v20, v125
	v_mov_b32_e32 v19, v125
	v_mov_b32_e32 v18, v125
	v_mov_b32_e32 v9, v125
	v_mov_b32_e32 v8, v125
	v_mov_b32_e32 v7, v125
	v_mov_b32_e32 v6, v125
	v_mov_b32_e32 v5, v125
	v_mov_b32_e32 v4, v125
	v_mov_b32_e32 v3, v125
	v_mov_b32_e32 v2, v125
	s_cbranch_vccnz .LBB0_961
	s_add_u32 s12, s12, 0x80
	s_addc_u32 s13, s13, 0
	s_add_u32 s42, s14, 0x100
	s_addc_u32 s43, s15, 0
	s_mov_b32 s14, 0
